# combine loop: zz gate load hoisted to loop top, 4th oB load issued before first wait (counted waits)
# speedup vs baseline: 1.0125x; 1.0125x over previous
; __device__ __forceinline__ float bflo(unsigned u) { return __uint_as_float(u << 16); }
; __device__ __forceinline__ float bfhi(unsigned u) { return __uint_as_float(u & 0xffff0000u); }
; __device__ __forceinline__ unsigned cvt_pk_bf16(float lo, float hi) { unsigned r; asm volatile("s_nop 0\n\tv_cvt_pk_bf16_f32 %0, %1, %2" : "=v"(r) : "v"(lo), "v"(hi)); return r; }
; __device__ __forceinline__ float siluf_(float x) { return x * sigmoidf_(x); }
; __device__ __forceinline__ f32x4 ld4bf(const bf16_t* p) { const u32x2 u = *(const u32x2*)p; return (f32x4){bflo(u.x), bfhi(u.x), bflo(u.y), bfhi(u.y)}; }
; __device__ __forceinline__ void phase_combine(KP P) {
;     ...
;     for (int idx = ((int)blockIdx.x - skip) * 512 + tid; idx < SEQ * 256; idx += ((int)gridDim.x - skip) * 512) {
;         const int s = idx >> 8, cg4 = idx & 255, br = cg4 >> 7, c4 = (cg4 & 127) * 4, j = c4 >> 7;
;         f32x4 o; u32x2 zz;
;         if (br == 0) {
;             const float l0 = lA[s * 4 + j], l1 = lA[(SEQ + s) * 4 + j], l2 = lA[(2 * SEQ + s) * 4 + j];
;             const float mx = fmaxf(l0, fmaxf(l1, l2)); const float w0 = __expf(l0 - mx), w1 = __expf(l1 - mx), w2 = __expf(l2 - mx); const float inv = 1.f / (w0 + w1 + w2);
;             const f32x4 a = ld4bf(oA + (size_t)s * 512 + c4), b = ld4bf(oA + ((size_t)SEQ + s) * 512 + c4), c = ld4bf(oA + ((size_t)2 * SEQ + s) * 512 + c4);
;             o = (a * w0 + b * w1 + c * w2) * inv;
;             zz = *(const u32x2*)(proj + (size_t)s * NP + O_AZ + c4);
;         } else {
;             const float l0 = lB[s * 4 + j], l1 = lB[(SEQ + s) * 4 + j];
;             const float mx = fmaxf(l0, l1); const float w0 = __expf(l0 - mx), w1 = __expf(l1 - mx); const float inv = 1.f / (w0 + w1);
;             const f32x4 a = ld4bf(oB + (size_t)s * 512 + c4), b = ld4bf(oB + ((size_t)SEQ + s) * 512 + c4);
;             o = (a * w0 + b * w1) * inv;
;             zz = *(const u32x2*)(proj + (size_t)s * NP + O_BZ + c4);
;         }
;         u32x2 w; w.x = cvt_pk_bf16(o[0] * siluf_(bflo(zz.x)), o[1] * siluf_(bfhi(zz.x))); w.y = cvt_pk_bf16(o[2] * siluf_(bflo(zz.y)), o[3] * siluf_(bfhi(zz.y)));
;         *(u32x2*)(ys + (size_t)s * DM + br * 512 + c4) = w;
.LBB0_1309:
	s_or_b64 exec, exec, s[20:21]
	v_pk_fma_f32 v[2:3], v[0:1], v[2:3], v[6:7] op_sel_hi:[0,1,1]
	v_pk_fma_f32 v[4:5], v[0:1], v[4:5], v[8:9] op_sel_hi:[0,1,1]
	v_lshlrev_b32_e32 v0, 1, v12
	v_div_scale_f32 v16, s[20:21], v21, v21, 1.0
	v_rcp_f32_e32 v18, v16
	v_bfe_u32 v17, v13, 7, 1
	v_add_u32_e32 v13, s23, v13
	s_mov_b32 s20, 0x1fffff
	v_fma_f32 v19, -v16, v18, 1.0
	v_fmac_f32_e32 v18, v19, v18
	v_div_scale_f32 v19, vcc, 1.0, v21, 1.0
	v_mul_f32_e32 v22, v19, v18
	v_fma_f32 v23, -v16, v22, v19
	v_fmac_f32_e32 v22, v23, v18
	v_fma_f32 v16, -v16, v22, v19
	v_div_fmas_f32 v16, v16, v18, v22
	v_div_fixup_f32 v16, v16, v21, 1.0
	v_pk_mul_f32 v[2:3], v[2:3], v[16:17] op_sel_hi:[1,0]
	v_pk_mul_f32 v[4:5], v[4:5], v[16:17] op_sel_hi:[1,0]
	v_cmp_lt_i32_e32 vcc, s20, v13
	v_add_u32_e32 v20, s4, v20
	s_or_b64 s[46:47], vcc, s[46:47]
	s_waitcnt vmcnt(0)
	v_mov_b32_e32 v6, v24
	v_mov_b32_e32 v7, v25
	v_lshlrev_b32_e32 v8, 16, v6
	v_mul_f32_e32 v9, 0xbfb8aa3b, v8
	v_exp_f32_e32 v9, v9
	v_and_b32_e32 v6, 0xffff0000, v6
	v_add_f32_e32 v9, 1.0, v9
	v_rcp_f32_e32 v9, v9
	s_nop 0
	v_mul_f32_e32 v8, v9, v8
	v_mul_f32_e32 v2, v2, v8
	v_mul_f32_e32 v8, 0xbfb8aa3b, v6
	v_exp_f32_e32 v8, v8
	s_nop 0
	v_add_f32_e32 v8, 1.0, v8
	v_rcp_f32_e32 v8, v8
	s_nop 0
	v_mul_f32_e32 v6, v8, v6
	v_mul_f32_e32 v3, v3, v6
	s_nop 0
	v_cvt_pk_bf16_f32 v2, v2, v3
	v_lshlrev_b32_e32 v3, 16, v7
	v_mul_f32_e32 v6, 0xbfb8aa3b, v3
	v_exp_f32_e32 v6, v6
	s_nop 0
	v_add_f32_e32 v6, 1.0, v6
	v_rcp_f32_e32 v6, v6
	s_nop 0
	v_mul_f32_e32 v3, v6, v3
	v_mul_f32_e32 v3, v4, v3
	v_and_b32_e32 v4, 0xffff0000, v7
	v_mul_f32_e32 v6, 0xbfb8aa3b, v4
	v_exp_f32_e32 v6, v6
	v_mov_b32_e32 v7, v1
	v_add_f32_e32 v6, 1.0, v6
	v_rcp_f32_e32 v6, v6
	s_nop 0
	v_mul_f32_e32 v4, v6, v4
	v_mul_f32_e32 v4, v5, v4
	s_nop 0
	v_cvt_pk_bf16_f32 v3, v3, v4
	v_lshlrev_b64 v[4:5], 12, v[10:11]
	v_lshl_add_u64 v[4:5], s[24:25], 0, v[4:5]
	v_lshlrev_b32_e32 v6, 10, v17
	v_lshl_add_u64 v[4:5], v[4:5], 0, v[6:7]
	v_lshl_add_u64 v[4:5], v[4:5], 0, v[0:1]
	global_store_dwordx2 v[4:5], v[2:3], off
	s_andn2_b64 exec, exec, s[46:47]
	s_cbranch_execz .LBB0_1314
.LBB0_1310:
	v_ashrrev_i32_e32 v10, 8, v13
	v_bfe_u32 v22, v20, 7, 2
	v_lshlrev_b32_e32 v23, 2, v10
	v_or_b32_e32 v16, v22, v23
	v_and_b32_e32 v0, 0x80, v13
	v_add_u32_e32 v18, 0x8000, v16
	v_and_b32_e32 v12, 0x1fc, v20
	v_cmp_ne_u32_e32 vcc, 0, v0
	v_mov_b32_e32 v28, 0x2400
	v_mov_b32_e32 v29, 0x2d00
	v_mul_hi_i32_i24_e32 v25, 0x8a00, v10
	v_mul_i32_i24_e32 v24, 0x8a00, v10
	v_cndmask_b32_e32 v26, v28, v29, vcc
	v_mov_b32_e32 v27, 0
	v_lshl_add_u64 v[24:25], s[6:7], 0, v[24:25]
	v_lshlrev_b32_e32 v28, 1, v12
	v_mov_b32_e32 v29, 0
	v_lshl_add_u64 v[24:25], v[24:25], 0, v[26:27]
	v_ashrrev_i32_e32 v17, 31, v16
	v_lshl_add_u64 v[24:25], v[24:25], 0, v[28:29]
	v_ashrrev_i32_e32 v19, 31, v18
	v_ashrrev_i32_e32 v11, 31, v10
	global_load_dwordx2 v[24:25], v[24:25], off
	s_and_saveexec_b64 s[20:21], vcc
	s_xor_b64 s[20:21], exec, s[20:21]
	s_cbranch_execz .LBB0_1312
	v_lshl_add_u64 v[2:3], v[16:17], 2, s[44:45]
	v_lshl_add_u64 v[4:5], v[18:19], 2, s[44:45]
	global_load_dword v8, v[2:3], off
	global_load_dword v9, v[4:5], off
	v_lshlrev_b64 v[2:3], 10, v[10:11]
	v_lshl_add_u64 v[2:3], s[42:43], 0, v[2:3]
	v_lshlrev_b32_e32 v0, 1, v12
	v_lshl_add_u64 v[2:3], v[2:3], 0, v[0:1]
	global_load_dwordx2 v[4:5], v[2:3], off
	v_add_co_u32_e32 v2, vcc, s29, v2
	s_nop 1
	v_addc_co_u32_e32 v3, vcc, 0, v3, vcc
	global_load_dwordx2 v[6:7], v[2:3], off
	s_waitcnt vmcnt(2)
	v_max_f32_e32 v0, v9, v9
	v_max_f32_e32 v2, v8, v8
	v_max_f32_e32 v0, v2, v0
	v_sub_f32_e32 v2, v8, v0
	v_sub_f32_e32 v0, v9, v0
	v_mul_f32_e32 v3, 0x3fb8aa3b, v2
	v_mul_f32_e32 v0, 0x3fb8aa3b, v0
	v_exp_f32_e32 v16, v3
	v_exp_f32_e32 v0, v0
	s_waitcnt vmcnt(1)
	v_lshlrev_b32_e32 v14, 16, v4
	v_and_b32_e32 v15, 0xffff0000, v4
	v_lshlrev_b32_e32 v8, 16, v5
	v_and_b32_e32 v9, 0xffff0000, v5
	v_add_f32_e32 v21, v16, v0
	v_pk_mul_f32 v[8:9], v[16:17], v[8:9] op_sel_hi:[0,1]
	s_waitcnt vmcnt(0)
	v_lshlrev_b32_e32 v2, 16, v6
	v_and_b32_e32 v3, 0xffff0000, v6
	v_lshlrev_b32_e32 v4, 16, v7
	v_and_b32_e32 v5, 0xffff0000, v7
	v_pk_mul_f32 v[6:7], v[16:17], v[14:15] op_sel_hi:[0,1]
